# v1 + GEMM4a epilogue: SSKV row-stat loads prefetched in last K iteration, counted wait
# baseline (speedup 1.0000x reference)
.LBB0_744:
	s_add_u32 s54, s42, s48
	s_addc_u32 s55, s43, s49
	s_add_u32 s52, s54, 0x100
	s_addc_u32 s53, s55, 0
	s_and_b64 s[50:51], s[46:47], exec
	s_cselect_b32 s51, s35, s53
	s_cselect_b32 s50, s82, s52
	s_add_u32 s48, s40, s48
	s_addc_u32 s49, s41, s49
	s_add_u32 s48, s48, 0x100
	s_addc_u32 s49, s49, 0
	s_and_b64 s[46:47], s[46:47], exec
	s_cselect_b32 s53, s31, s49
	s_cselect_b32 s52, s83, s48
	s_cselect_b32 s98, 1, 0
	s_add_u32 s56, s54, 0x10080
	ds_read_b128 v[150:153], v144
	ds_read_b128 v[154:157], v144 offset:1024
	ds_read_b128 v[158:161], v144 offset:2048
	ds_read_b128 v[162:165], v144 offset:3072
	ds_read_b128 v[166:169], v145
	ds_read_b128 v[170:173], v145 offset:1024
	ds_read_b128 v[174:177], v145 offset:2048
	ds_read_b128 v[178:181], v145 offset:3072
	s_addc_u32 s57, s55, 0
	s_add_i32 s93, s74, s60
	s_add_i32 m0, s61, 0xc000
	s_add_i32 s94, s61, 0xe000
	s_add_i32 s90, s93, 0x2000
	s_add_u32 s54, s52, 0x10000
	s_addc_u32 s55, s53, 0
	s_add_i32 s92, s75, s60
	s_add_i32 s91, s92, 0x2000
	s_add_i32 s89, 0, 0x18000
	s_add_i32 s88, 0, 0x1c000
	s_add_u32 s48, s50, 0x10000
	s_addc_u32 s49, s51, 0
	s_add_i32 s87, s89, s60
	s_add_i32 s85, s87, 0x2000
	s_add_u32 s46, s52, 0x10080
	s_addc_u32 s47, s53, 0
	s_add_i32 s86, s88, s60
	s_add_i32 s84, s86, 0x2000
	v_lshl_add_u64 v[138:139], s[56:57], 0, v[130:131]
	ds_read_b128 v[182:185], v146
	ds_read_b128 v[186:189], v146 offset:1024
	ds_read_b128 v[190:193], v146 offset:2048
	ds_read_b128 v[194:197], v146 offset:3072
	ds_read_b128 v[198:201], v146 offset:4096
	ds_read_b128 v[202:205], v146 offset:5120
	ds_read_b128 v[206:209], v146 offset:6144
	ds_read_b128 v[210:213], v146 offset:7168
	global_load_lds_dwordx4 v[138:139], off
	v_lshl_add_u64 v[138:139], s[56:57], 0, v[128:129]
	s_mov_b32 m0, s94
	s_nop 0
	global_load_lds_dwordx4 v[138:139], off
	s_waitcnt vmcnt(8)
	s_waitcnt lgkmcnt(0)
	s_barrier
	s_cmp_lg_u32 s98, 0
	s_cbranch_scc0 .Lkv_nopf
	v_lshl_add_u32 v138, s18, 8, v141
	v_ashrrev_i32_e32 v139, 31, v138
	v_lshl_add_u64 v[138:139], v[138:139], 4, s[14:15]
	global_load_dwordx4 v[222:225], v[138:139], off
	global_load_dwordx4 v[226:229], v[138:139], off offset:256
	global_load_dwordx4 v[230:233], v[138:139], off offset:512
	global_load_dwordx4 v[234:237], v[138:139], off offset:768
	global_load_dwordx4 v[238:241], v[138:139], off offset:2048
	global_load_dwordx4 v[242:245], v[138:139], off offset:2304
	global_load_dwordx4 v[248:251], v[138:139], off offset:2560
	global_load_dwordx4 v[252:255], v[138:139], off offset:2816
.Lkv_nopf:
	s_setprio 1
	s_waitcnt lgkmcnt(0)
	v_mfma_f32_16x16x32_bf16 v[124:127], v[150:153], v[182:185], v[124:127]
	v_mfma_f32_16x16x32_bf16 v[120:123], v[158:161], v[182:185], v[120:123]
	v_mfma_f32_16x16x32_bf16 v[108:111], v[150:153], v[190:193], v[108:111]
	v_mfma_f32_16x16x32_bf16 v[104:107], v[158:161], v[190:193], v[104:107]
	v_mfma_f32_16x16x32_bf16 v[92:95], v[150:153], v[198:201], v[92:95]
	v_mfma_f32_16x16x32_bf16 v[88:91], v[158:161], v[198:201], v[88:91]
	v_mfma_f32_16x16x32_bf16 v[76:79], v[150:153], v[206:209], v[76:79]
	v_mfma_f32_16x16x32_bf16 v[72:75], v[158:161], v[206:209], v[72:75]
	v_mfma_f32_16x16x32_bf16 v[124:127], v[154:157], v[186:189], v[124:127]
	v_mfma_f32_16x16x32_bf16 v[120:123], v[162:165], v[186:189], v[120:123]
	v_mfma_f32_16x16x32_bf16 v[108:111], v[154:157], v[194:197], v[108:111]
	v_mfma_f32_16x16x32_bf16 v[104:107], v[162:165], v[194:197], v[104:107]
	v_mfma_f32_16x16x32_bf16 v[92:95], v[154:157], v[202:205], v[92:95]
	v_mfma_f32_16x16x32_bf16 v[88:91], v[162:165], v[202:205], v[88:91]
	v_mfma_f32_16x16x32_bf16 v[76:79], v[154:157], v[210:213], v[76:79]
	v_mfma_f32_16x16x32_bf16 v[72:75], v[162:165], v[210:213], v[72:75]
	s_setprio 0
	s_setprio 1
	v_mfma_f32_16x16x32_bf16 v[116:119], v[166:169], v[182:185], v[116:119]
	v_mfma_f32_16x16x32_bf16 v[112:115], v[174:177], v[182:185], v[112:115]
	v_mfma_f32_16x16x32_bf16 v[100:103], v[166:169], v[190:193], v[100:103]
	v_mfma_f32_16x16x32_bf16 v[96:99], v[174:177], v[190:193], v[96:99]
	v_mfma_f32_16x16x32_bf16 v[84:87], v[166:169], v[198:201], v[84:87]
	v_mfma_f32_16x16x32_bf16 v[80:83], v[174:177], v[198:201], v[80:83]
	v_mfma_f32_16x16x32_bf16 v[68:71], v[166:169], v[206:209], v[68:71]
	v_mfma_f32_16x16x32_bf16 v[64:67], v[174:177], v[206:209], v[64:67]
	v_mfma_f32_16x16x32_bf16 v[116:119], v[170:173], v[186:189], v[116:119]
	v_mfma_f32_16x16x32_bf16 v[112:115], v[178:181], v[186:189], v[112:115]
	v_mfma_f32_16x16x32_bf16 v[100:103], v[170:173], v[194:197], v[100:103]
	v_mfma_f32_16x16x32_bf16 v[96:99], v[178:181], v[194:197], v[96:99]
	v_mfma_f32_16x16x32_bf16 v[84:87], v[170:173], v[202:205], v[84:87]
	v_mfma_f32_16x16x32_bf16 v[80:83], v[178:181], v[202:205], v[80:83]
	v_mfma_f32_16x16x32_bf16 v[68:71], v[170:173], v[210:213], v[68:71]
	v_mfma_f32_16x16x32_bf16 v[64:67], v[178:181], v[210:213], v[64:67]
	s_setprio 0
	s_barrier
	s_mov_b32 m0, s93
	v_lshl_add_u64 v[138:139], s[52:53], 0, v[130:131]
	ds_read_b128 v[182:185], v146 offset:16384
	ds_read_b128 v[186:189], v146 offset:17408
	ds_read_b128 v[190:193], v146 offset:18432
	ds_read_b128 v[194:197], v146 offset:19456
	ds_read_b128 v[198:201], v146 offset:20480
	ds_read_b128 v[202:205], v146 offset:21504
	ds_read_b128 v[206:209], v146 offset:22528
	ds_read_b128 v[210:213], v146 offset:23552
	global_load_lds_dwordx4 v[138:139], off
	v_lshl_add_u64 v[214:215], s[52:53], 0, v[128:129]
	s_mov_b32 m0, s90
	v_lshl_add_u64 v[216:217], s[54:55], 0, v[130:131]
	global_load_lds_dwordx4 v[214:215], off
	s_mov_b32 m0, s92
	v_lshl_add_u64 v[218:219], s[50:51], 0, v[128:129]
	global_load_lds_dwordx4 v[216:217], off
	v_lshl_add_u64 v[216:217], s[54:55], 0, v[128:129]
	s_mov_b32 m0, s91
	s_nop 0
	global_load_lds_dwordx4 v[216:217], off
	v_lshl_add_u64 v[216:217], s[50:51], 0, v[130:131]
	s_mov_b32 m0, s61
	s_nop 0
	global_load_lds_dwordx4 v[216:217], off
	s_mov_b32 m0, s62
	s_nop 0
	global_load_lds_dwordx4 v[218:219], off
	s_waitcnt vmcnt(8)
	s_waitcnt lgkmcnt(0)
	s_barrier
	s_setprio 1
	s_waitcnt lgkmcnt(0)
	v_mfma_f32_16x16x32_bf16 v[60:63], v[150:153], v[182:185], v[60:63]
	v_mfma_f32_16x16x32_bf16 v[56:59], v[158:161], v[182:185], v[56:59]
	v_mfma_f32_16x16x32_bf16 v[44:47], v[150:153], v[190:193], v[44:47]
	v_mfma_f32_16x16x32_bf16 v[40:43], v[158:161], v[190:193], v[40:43]
	v_mfma_f32_16x16x32_bf16 v[28:31], v[150:153], v[198:201], v[28:31]
	v_mfma_f32_16x16x32_bf16 v[24:27], v[158:161], v[198:201], v[24:27]
	v_mfma_f32_16x16x32_bf16 v[12:15], v[150:153], v[206:209], v[12:15]
	v_mfma_f32_16x16x32_bf16 v[8:11], v[158:161], v[206:209], v[8:11]
	v_mfma_f32_16x16x32_bf16 v[60:63], v[154:157], v[186:189], v[60:63]
	v_mfma_f32_16x16x32_bf16 v[56:59], v[162:165], v[186:189], v[56:59]
	v_mfma_f32_16x16x32_bf16 v[44:47], v[154:157], v[194:197], v[44:47]
	v_mfma_f32_16x16x32_bf16 v[40:43], v[162:165], v[194:197], v[40:43]
	v_mfma_f32_16x16x32_bf16 v[28:31], v[154:157], v[202:205], v[28:31]
	v_mfma_f32_16x16x32_bf16 v[24:27], v[162:165], v[202:205], v[24:27]
	v_mfma_f32_16x16x32_bf16 v[12:15], v[154:157], v[210:213], v[12:15]
	v_mfma_f32_16x16x32_bf16 v[8:11], v[162:165], v[210:213], v[8:11]
	s_setprio 0
	s_setprio 1
	v_mfma_f32_16x16x32_bf16 v[52:55], v[166:169], v[182:185], v[52:55]
	v_mfma_f32_16x16x32_bf16 v[48:51], v[174:177], v[182:185], v[48:51]
	v_mfma_f32_16x16x32_bf16 v[36:39], v[166:169], v[190:193], v[36:39]
	v_mfma_f32_16x16x32_bf16 v[32:35], v[174:177], v[190:193], v[32:35]
	v_mfma_f32_16x16x32_bf16 v[20:23], v[166:169], v[198:201], v[20:23]
	v_mfma_f32_16x16x32_bf16 v[16:19], v[174:177], v[198:201], v[16:19]
	v_mfma_f32_16x16x32_bf16 v[4:7], v[166:169], v[206:209], v[4:7]
	v_mfma_f32_16x16x32_bf16 v[0:3], v[174:177], v[206:209], v[0:3]
	v_mfma_f32_16x16x32_bf16 v[52:55], v[170:173], v[186:189], v[52:55]
	v_mfma_f32_16x16x32_bf16 v[48:51], v[178:181], v[186:189], v[48:51]
	v_mfma_f32_16x16x32_bf16 v[36:39], v[170:173], v[194:197], v[36:39]
	v_mfma_f32_16x16x32_bf16 v[32:35], v[178:181], v[194:197], v[32:35]
	v_mfma_f32_16x16x32_bf16 v[20:23], v[170:173], v[202:205], v[20:23]
	v_mfma_f32_16x16x32_bf16 v[16:19], v[178:181], v[202:205], v[16:19]
	v_mfma_f32_16x16x32_bf16 v[4:7], v[170:173], v[210:213], v[4:7]
	v_mfma_f32_16x16x32_bf16 v[0:3], v[178:181], v[210:213], v[0:3]
	s_setprio 0
	s_barrier
	v_add_u32_e32 v132, s89, v143
	ds_read_b128 v[150:153], v132
	ds_read_b128 v[154:157], v132 offset:1024
	ds_read_b128 v[158:161], v132 offset:2048
	ds_read_b128 v[162:165], v132 offset:3072
	v_add_u32_e32 v132, s88, v143
	ds_read_b128 v[166:169], v132
	ds_read_b128 v[170:173], v132 offset:1024
	ds_read_b128 v[174:177], v132 offset:2048
	ds_read_b128 v[178:181], v132 offset:3072
	s_mov_b32 m0, s63
	v_lshl_add_u64 v[220:221], s[48:49], 0, v[130:131]
	ds_read_b128 v[182:185], v146 offset:32768
	ds_read_b128 v[186:189], v146 offset:33792
	ds_read_b128 v[190:193], v146 offset:34816
	ds_read_b128 v[194:197], v146 offset:35840
	ds_read_b128 v[198:201], v146 offset:36864
	ds_read_b128 v[202:205], v146 offset:37888
	ds_read_b128 v[206:209], v146 offset:38912
	ds_read_b128 v[210:213], v146 offset:39936
	global_load_lds_dwordx4 v[220:221], off
	v_lshl_add_u64 v[220:221], s[48:49], 0, v[128:129]
	s_mov_b32 m0, s64
	s_nop 0
	global_load_lds_dwordx4 v[220:221], off
	s_waitcnt vmcnt(8)
	s_waitcnt lgkmcnt(0)
	s_barrier
	s_setprio 1
	s_waitcnt lgkmcnt(0)
	v_mfma_f32_16x16x32_bf16 v[124:127], v[150:153], v[182:185], v[124:127]
	v_mfma_f32_16x16x32_bf16 v[120:123], v[158:161], v[182:185], v[120:123]
	v_mfma_f32_16x16x32_bf16 v[108:111], v[150:153], v[190:193], v[108:111]
	v_mfma_f32_16x16x32_bf16 v[104:107], v[158:161], v[190:193], v[104:107]
	v_mfma_f32_16x16x32_bf16 v[92:95], v[150:153], v[198:201], v[92:95]
	v_mfma_f32_16x16x32_bf16 v[88:91], v[158:161], v[198:201], v[88:91]
	v_mfma_f32_16x16x32_bf16 v[76:79], v[150:153], v[206:209], v[76:79]
	v_mfma_f32_16x16x32_bf16 v[72:75], v[158:161], v[206:209], v[72:75]
	v_mfma_f32_16x16x32_bf16 v[124:127], v[154:157], v[186:189], v[124:127]
	v_mfma_f32_16x16x32_bf16 v[120:123], v[162:165], v[186:189], v[120:123]
	v_mfma_f32_16x16x32_bf16 v[108:111], v[154:157], v[194:197], v[108:111]
	v_mfma_f32_16x16x32_bf16 v[104:107], v[162:165], v[194:197], v[104:107]
	v_mfma_f32_16x16x32_bf16 v[92:95], v[154:157], v[202:205], v[92:95]
	v_mfma_f32_16x16x32_bf16 v[88:91], v[162:165], v[202:205], v[88:91]
	v_mfma_f32_16x16x32_bf16 v[76:79], v[154:157], v[210:213], v[76:79]
	v_mfma_f32_16x16x32_bf16 v[72:75], v[162:165], v[210:213], v[72:75]
	s_setprio 0
	s_setprio 1
	v_mfma_f32_16x16x32_bf16 v[116:119], v[166:169], v[182:185], v[116:119]
	v_mfma_f32_16x16x32_bf16 v[112:115], v[174:177], v[182:185], v[112:115]
	v_mfma_f32_16x16x32_bf16 v[100:103], v[166:169], v[190:193], v[100:103]
	v_mfma_f32_16x16x32_bf16 v[96:99], v[174:177], v[190:193], v[96:99]
	v_mfma_f32_16x16x32_bf16 v[84:87], v[166:169], v[198:201], v[84:87]
	v_mfma_f32_16x16x32_bf16 v[80:83], v[174:177], v[198:201], v[80:83]
	v_mfma_f32_16x16x32_bf16 v[68:71], v[166:169], v[206:209], v[68:71]
	v_mfma_f32_16x16x32_bf16 v[64:67], v[174:177], v[206:209], v[64:67]
	v_mfma_f32_16x16x32_bf16 v[116:119], v[170:173], v[186:189], v[116:119]
	v_mfma_f32_16x16x32_bf16 v[112:115], v[178:181], v[186:189], v[112:115]
	v_mfma_f32_16x16x32_bf16 v[100:103], v[170:173], v[194:197], v[100:103]
	v_mfma_f32_16x16x32_bf16 v[96:99], v[178:181], v[194:197], v[96:99]
	v_mfma_f32_16x16x32_bf16 v[84:87], v[170:173], v[202:205], v[84:87]
	v_mfma_f32_16x16x32_bf16 v[80:83], v[178:181], v[202:205], v[80:83]
	v_mfma_f32_16x16x32_bf16 v[68:71], v[170:173], v[210:213], v[68:71]
	v_mfma_f32_16x16x32_bf16 v[64:67], v[178:181], v[210:213], v[64:67]
	s_setprio 0
	s_barrier
	s_mov_b32 m0, s87
	v_lshl_add_u64 v[138:139], v[138:139], 0, s[16:17]
	ds_read_b128 v[182:185], v146 offset:49152
	ds_read_b128 v[186:189], v146 offset:50176
	ds_read_b128 v[190:193], v146 offset:51200
	ds_read_b128 v[194:197], v146 offset:52224
	ds_read_b128 v[198:201], v146 offset:53248
	ds_read_b128 v[202:205], v146 offset:54272
	ds_read_b128 v[206:209], v146 offset:55296
	ds_read_b128 v[210:213], v146 offset:56320
	global_load_lds_dwordx4 v[138:139], off
	v_lshl_add_u64 v[138:139], v[214:215], 0, s[16:17]
	s_mov_b32 m0, s85
	s_nop 0
	global_load_lds_dwordx4 v[138:139], off
	v_lshl_add_u64 v[138:139], s[46:47], 0, v[130:131]
	s_mov_b32 m0, s86
	s_nop 0
	global_load_lds_dwordx4 v[138:139], off
	v_lshl_add_u64 v[138:139], s[46:47], 0, v[128:129]
	s_mov_b32 m0, s84
	s_nop 0
	global_load_lds_dwordx4 v[138:139], off
	v_lshl_add_u64 v[138:139], v[216:217], 0, s[16:17]
	s_mov_b32 m0, s70
	s_nop 0
	global_load_lds_dwordx4 v[138:139], off
	v_lshl_add_u64 v[138:139], v[218:219], 0, s[16:17]
	s_mov_b32 m0, s71
	s_nop 0
	global_load_lds_dwordx4 v[138:139], off
	s_waitcnt vmcnt(8)
	s_waitcnt lgkmcnt(0)
	s_barrier
	s_setprio 1
	s_waitcnt lgkmcnt(0)
	v_mfma_f32_16x16x32_bf16 v[60:63], v[150:153], v[182:185], v[60:63]
	v_mfma_f32_16x16x32_bf16 v[56:59], v[158:161], v[182:185], v[56:59]
	v_mfma_f32_16x16x32_bf16 v[44:47], v[150:153], v[190:193], v[44:47]
	v_mfma_f32_16x16x32_bf16 v[40:43], v[158:161], v[190:193], v[40:43]
	v_mfma_f32_16x16x32_bf16 v[28:31], v[150:153], v[198:201], v[28:31]
	v_mfma_f32_16x16x32_bf16 v[24:27], v[158:161], v[198:201], v[24:27]
	v_mfma_f32_16x16x32_bf16 v[12:15], v[150:153], v[206:209], v[12:15]
	v_mfma_f32_16x16x32_bf16 v[8:11], v[158:161], v[206:209], v[8:11]
	v_mfma_f32_16x16x32_bf16 v[60:63], v[154:157], v[186:189], v[60:63]
	v_mfma_f32_16x16x32_bf16 v[56:59], v[162:165], v[186:189], v[56:59]
	v_mfma_f32_16x16x32_bf16 v[44:47], v[154:157], v[194:197], v[44:47]
	v_mfma_f32_16x16x32_bf16 v[40:43], v[162:165], v[194:197], v[40:43]
	v_mfma_f32_16x16x32_bf16 v[28:31], v[154:157], v[202:205], v[28:31]
	v_mfma_f32_16x16x32_bf16 v[24:27], v[162:165], v[202:205], v[24:27]
	v_mfma_f32_16x16x32_bf16 v[12:15], v[154:157], v[210:213], v[12:15]
	v_mfma_f32_16x16x32_bf16 v[8:11], v[162:165], v[210:213], v[8:11]
	s_setprio 0
	s_setprio 1
	v_mfma_f32_16x16x32_bf16 v[52:55], v[166:169], v[182:185], v[52:55]
	v_mfma_f32_16x16x32_bf16 v[48:51], v[174:177], v[182:185], v[48:51]
	v_mfma_f32_16x16x32_bf16 v[36:39], v[166:169], v[190:193], v[36:39]
	v_mfma_f32_16x16x32_bf16 v[32:35], v[174:177], v[190:193], v[32:35]
	v_mfma_f32_16x16x32_bf16 v[20:23], v[166:169], v[198:201], v[20:23]
	v_mfma_f32_16x16x32_bf16 v[16:19], v[174:177], v[198:201], v[16:19]
	v_mfma_f32_16x16x32_bf16 v[4:7], v[166:169], v[206:209], v[4:7]
	v_mfma_f32_16x16x32_bf16 v[0:3], v[174:177], v[206:209], v[0:3]
	v_mfma_f32_16x16x32_bf16 v[52:55], v[170:173], v[186:189], v[52:55]
	v_mfma_f32_16x16x32_bf16 v[48:51], v[178:181], v[186:189], v[48:51]
	v_mfma_f32_16x16x32_bf16 v[36:39], v[170:173], v[194:197], v[36:39]
	v_mfma_f32_16x16x32_bf16 v[32:35], v[178:181], v[194:197], v[32:35]
	v_mfma_f32_16x16x32_bf16 v[20:23], v[170:173], v[202:205], v[20:23]
	v_mfma_f32_16x16x32_bf16 v[16:19], v[178:181], v[202:205], v[16:19]
	v_mfma_f32_16x16x32_bf16 v[4:7], v[170:173], v[210:213], v[4:7]
	v_mfma_f32_16x16x32_bf16 v[0:3], v[178:181], v[210:213], v[0:3]
	s_setprio 0
	s_barrier
	s_andn2_b64 vcc, exec, s[44:45]
	s_mov_b64 s[46:47], -1
	s_mov_b64 s[44:45], 0
	s_mov_b64 s[48:49], 0x100
	s_cbranch_vccz .LBB0_744
	s_and_b64 vcc, exec, s[20:21]
	s_cbranch_vccz .LBB0_747
	s_barrier

.LBB0_752:
	v_lshl_add_u32 v178, s18, 8, v141
	v_or_b32_e32 v152, 16, v178
	v_ashrrev_i32_e32 v179, 31, v178
	v_ashrrev_i32_e32 v153, 31, v152
	v_lshl_add_u64 v[150:151], v[178:179], 4, s[14:15]
	v_lshl_add_u64 v[154:155], v[152:153], 4, s[14:15]
	v_or_b32_e32 v158, 32, v178
	v_or_b32_e32 v160, 48, v178
	v_ashrrev_i32_e32 v159, 31, v158
	v_ashrrev_i32_e32 v161, 31, v160
	v_add_u32_e32 v166, 0x80, v178
	v_add_u32_e32 v168, 0x90, v178
	v_lshl_add_u64 v[158:159], v[158:159], 4, s[14:15]
	v_lshl_add_u64 v[162:163], v[160:161], 4, s[14:15]
	v_ashrrev_i32_e32 v167, 31, v166
	v_ashrrev_i32_e32 v169, 31, v168
	v_lshl_add_u64 v[166:167], v[166:167], 4, s[14:15]
	v_lshl_add_u64 v[170:171], v[168:169], 4, s[14:15]
	v_add_u32_e32 v174, 0xa0, v178
	v_add_u32_e32 v178, 0xb0, v178
	v_ashrrev_i32_e32 v175, 31, v174
	v_ashrrev_i32_e32 v179, 31, v178
	v_lshl_add_u64 v[174:175], v[174:175], 4, s[14:15]
	v_lshl_add_u64 v[178:179], v[178:179], 4, s[14:15]
	v_lshrrev_b32_e32 v132, 3, v140
	v_and_b32_e32 v140, 0x70, v142
	v_mul_lo_u32 v132, v132, s73
	v_add3_u32 v149, s72, v132, v140
	s_lshl_b32 s18, s40, 1
	s_lshl_b32 s35, 1, s31
	s_lshl_b32 s40, s35, 1
	s_mov_b32 s41, s19
	s_lshl_b32 s35, 2, s31
	s_lshl_b32 s42, s35, 1
	s_mov_b32 s43, s19
	s_lshl_b32 s31, 3, s31
	s_lshl_b32 s44, s31, 1
	s_mov_b32 s45, s19
	s_mov_b64 s[46:47], 0x20000
	s_waitcnt vmcnt(14)
	v_mov_b64_e32 v[150:151], v[222:223]
	v_mov_b64_e32 v[152:153], v[224:225]
	v_mov_b64_e32 v[154:155], v[226:227]
	v_mov_b64_e32 v[156:157], v[228:229]
	v_mov_b64_e32 v[158:159], v[230:231]
	v_mov_b64_e32 v[160:161], v[232:233]
	v_mov_b64_e32 v[162:163], v[234:235]
	v_mov_b64_e32 v[164:165], v[236:237]
	v_mov_b64_e32 v[166:167], v[238:239]
	v_mov_b64_e32 v[168:169], v[240:241]
	v_mov_b64_e32 v[170:171], v[242:243]
	v_mov_b64_e32 v[172:173], v[244:245]
	v_mov_b64_e32 v[174:175], v[248:249]
	v_mov_b64_e32 v[176:177], v[250:251]
	v_mov_b64_e32 v[178:179], v[252:253]
	v_mov_b64_e32 v[180:181], v[254:255]
	v_mov_b32_e32 v182, v151
	v_mov_b32_e32 v183, v152
	v_mov_b32_e32 v151, v153
	v_pk_add_f32 v[150:151], v[182:183], v[150:151]
	v_mov_b32_e32 v152, v155
	v_mov_b32_e32 v153, v156
	v_mov_b32_e32 v155, v157
	v_add_f32_e32 v132, v150, v151
	v_pk_add_f32 v[150:151], v[152:153], v[154:155]
	v_fmamk_f32 v132, v132, 0x3b800000, v147
	v_add_f32_e32 v140, v150, v151
	v_mov_b32_e32 v156, v159
	v_mov_b32_e32 v157, v160
	v_mov_b32_e32 v159, v161
	v_mov_b32_e32 v160, v163
	v_mov_b32_e32 v161, v164
	v_mov_b32_e32 v163, v165
	v_mov_b32_e32 v164, v167
	v_mov_b32_e32 v165, v168
	v_mov_b32_e32 v167, v169
	v_rsq_f32_e32 v150, v132
	v_pk_add_f32 v[152:153], v[156:157], v[158:159]
	v_pk_add_f32 v[154:155], v[160:161], v[162:163]
	v_pk_add_f32 v[156:157], v[164:165], v[166:167]
	v_mov_b32_e32 v168, v171
	v_mov_b32_e32 v169, v172
	v_mov_b32_e32 v171, v173
	v_add_f32_e32 v142, v152, v153
	v_add_f32_e32 v151, v154, v155
	v_add_f32_e32 v152, v156, v157
	v_pk_add_f32 v[158:159], v[168:169], v[170:171]
	v_fmamk_f32 v132, v140, 0x3b800000, v147
	v_fmamk_f32 v140, v142, 0x3b800000, v147
	v_fmamk_f32 v142, v151, 0x3b800000, v147
	v_fmamk_f32 v151, v152, 0x3b800000, v147
	v_add_f32_e32 v153, v158, v159
	v_pk_mul_f32 v[124:125], v[124:125], v[150:151] op_sel_hi:[1,0]
	v_pk_mul_f32 v[158:159], v[122:123], v[150:151] op_sel_hi:[1,0]
	v_pk_mul_f32 v[122:123], v[120:121], v[150:151] op_sel_hi:[1,0]
	v_pk_mul_f32 v[126:127], v[126:127], v[150:151] op_sel_hi:[1,0]
	v_cvt_pk_bf16_f32 v120, v124, v125
	v_pk_mul_f32 v[124:125], v[114:115], v[150:151] op_sel_hi:[1,0]
	v_cvt_pk_bf16_f32 v121, v126, v127
	v_cvt_pk_bf16_f32 v122, v122, v123
	v_cvt_pk_bf16_f32 v123, v158, v159
	v_pk_mul_f32 v[114:115], v[112:113], v[150:151] op_sel_hi:[1,0]
	v_pk_mul_f32 v[118:119], v[118:119], v[150:151] op_sel_hi:[1,0]
	v_pk_mul_f32 v[116:117], v[116:117], v[150:151] op_sel_hi:[1,0]
	v_mov_b32_e32 v172, v175
	v_cvt_pk_bf16_f32 v112, v116, v117
	v_cvt_pk_bf16_f32 v113, v118, v119
	v_cvt_pk_bf16_f32 v114, v114, v115
	v_cvt_pk_bf16_f32 v115, v124, v125
	ds_write_b128 v148, v[120:123]
	ds_write_b128 v148, v[112:115] offset:64
	v_mov_b32_e32 v173, v176
	v_mov_b32_e32 v175, v177
	v_mov_b32_e32 v176, v179
	v_mov_b32_e32 v177, v180
	v_mov_b32_e32 v179, v181
	ds_read_b128 v[112:115], v149
	v_pk_add_f32 v[116:117], v[176:177], v[178:179]
	v_rsq_f32_e32 v152, v132
	v_add_f32_e32 v120, v116, v117
	ds_read_b128 v[116:119], v149 offset:1152
	v_fmamk_f32 v153, v153, 0x3b800000, v147
	s_waitcnt lgkmcnt(1)
	global_store_dwordx4 v[138:139], v[112:115], off nt
	v_pk_mul_f32 v[108:109], v[108:109], v[152:153] op_sel_hi:[1,0]
	v_pk_mul_f32 v[110:111], v[110:111], v[152:153] op_sel_hi:[1,0]
	v_lshl_add_u64 v[112:113], v[138:139], 0, s[18:19]
	s_waitcnt lgkmcnt(0)
	global_store_dwordx4 v[112:113], v[116:119], off nt
	v_pk_mul_f32 v[112:113], v[106:107], v[152:153] op_sel_hi:[1,0]
	v_pk_mul_f32 v[106:107], v[104:105], v[152:153] op_sel_hi:[1,0]
	v_cvt_pk_bf16_f32 v104, v108, v109
	v_cvt_pk_bf16_f32 v105, v110, v111
	v_pk_mul_f32 v[108:109], v[98:99], v[152:153] op_sel_hi:[1,0]
	v_cvt_pk_bf16_f32 v106, v106, v107
	v_cvt_pk_bf16_f32 v107, v112, v113
	v_pk_mul_f32 v[98:99], v[96:97], v[152:153] op_sel_hi:[1,0]
	v_pk_mul_f32 v[102:103], v[102:103], v[152:153] op_sel_hi:[1,0]
	v_pk_mul_f32 v[100:101], v[100:101], v[152:153] op_sel_hi:[1,0]
	v_pk_add_f32 v[160:161], v[172:173], v[174:175]
	v_cvt_pk_bf16_f32 v96, v100, v101
	v_cvt_pk_bf16_f32 v97, v102, v103
	v_cvt_pk_bf16_f32 v98, v98, v99
	v_cvt_pk_bf16_f32 v99, v108, v109
	ds_write_b128 v148, v[104:107]
	ds_write_b128 v148, v[96:99] offset:64
	v_add_f32_e32 v154, v160, v161
	ds_read_b128 v[96:99], v149
	ds_read_b128 v[100:103], v149 offset:1152
	v_fmamk_f32 v155, v154, 0x3b800000, v147
	v_rsq_f32_e32 v154, v140
	v_lshl_add_u64 v[104:105], v[138:139], 0, s[40:41]
	s_waitcnt lgkmcnt(1)
	global_store_dwordx4 v[104:105], v[96:99], off nt
	v_pk_mul_f32 v[92:93], v[92:93], v[154:155] op_sel_hi:[1,0]
	v_pk_mul_f32 v[94:95], v[94:95], v[154:155] op_sel_hi:[1,0]
	v_lshl_add_u64 v[96:97], v[104:105], 0, s[18:19]
	s_waitcnt lgkmcnt(0)
	global_store_dwordx4 v[96:97], v[100:103], off nt
	v_pk_mul_f32 v[96:97], v[90:91], v[154:155] op_sel_hi:[1,0]
	v_pk_mul_f32 v[90:91], v[88:89], v[154:155] op_sel_hi:[1,0]
	v_cvt_pk_bf16_f32 v88, v92, v93
	v_cvt_pk_bf16_f32 v89, v94, v95
	v_pk_mul_f32 v[92:93], v[82:83], v[154:155] op_sel_hi:[1,0]
	v_cvt_pk_bf16_f32 v90, v90, v91
	v_cvt_pk_bf16_f32 v91, v96, v97
	v_pk_mul_f32 v[82:83], v[80:81], v[154:155] op_sel_hi:[1,0]
	v_pk_mul_f32 v[86:87], v[86:87], v[154:155] op_sel_hi:[1,0]
	v_pk_mul_f32 v[84:85], v[84:85], v[154:155] op_sel_hi:[1,0]
	v_rsq_f32_e32 v156, v142
	v_cvt_pk_bf16_f32 v80, v84, v85
	v_cvt_pk_bf16_f32 v81, v86, v87
	v_cvt_pk_bf16_f32 v82, v82, v83
	v_cvt_pk_bf16_f32 v83, v92, v93
	ds_write_b128 v148, v[88:91]
	ds_write_b128 v148, v[80:83] offset:64
	ds_read_b128 v[80:83], v149
	ds_read_b128 v[84:87], v149 offset:1152
	v_lshl_add_u64 v[88:89], v[138:139], 0, s[42:43]
	v_pk_mul_f32 v[76:77], v[76:77], v[156:157] op_sel_hi:[1,0]
	s_waitcnt lgkmcnt(1)
	global_store_dwordx4 v[88:89], v[80:83], off nt
	v_pk_mul_f32 v[78:79], v[78:79], v[156:157] op_sel_hi:[1,0]
	v_pk_mul_f32 v[70:71], v[70:71], v[156:157] op_sel_hi:[1,0]
	v_lshl_add_u64 v[80:81], v[88:89], 0, s[18:19]
	s_waitcnt lgkmcnt(0)
	global_store_dwordx4 v[80:81], v[84:87], off nt
	v_pk_mul_f32 v[80:81], v[74:75], v[156:157] op_sel_hi:[1,0]
	v_pk_mul_f32 v[74:75], v[72:73], v[156:157] op_sel_hi:[1,0]
	v_cvt_pk_bf16_f32 v72, v76, v77
	v_cvt_pk_bf16_f32 v73, v78, v79
	v_pk_mul_f32 v[76:77], v[66:67], v[156:157] op_sel_hi:[1,0]
	v_cvt_pk_bf16_f32 v74, v74, v75
	v_cvt_pk_bf16_f32 v75, v80, v81
	v_pk_mul_f32 v[66:67], v[64:65], v[156:157] op_sel_hi:[1,0]
	v_pk_mul_f32 v[68:69], v[68:69], v[156:157] op_sel_hi:[1,0]
	v_rsq_f32_e32 v142, v151
	v_cvt_pk_bf16_f32 v64, v68, v69
	v_cvt_pk_bf16_f32 v65, v70, v71
	v_cvt_pk_bf16_f32 v66, v66, v67
	v_cvt_pk_bf16_f32 v67, v76, v77
	ds_write_b128 v148, v[72:75]
	ds_write_b128 v148, v[64:67] offset:64
	ds_read_b128 v[64:67], v149
	ds_read_b128 v[68:71], v149 offset:1152
	v_lshl_add_u64 v[72:73], v[138:139], 0, s[44:45]
	v_pk_mul_f32 v[60:61], v[60:61], v[142:143] op_sel_hi:[1,0]
	s_waitcnt lgkmcnt(1)
	global_store_dwordx4 v[72:73], v[64:67], off nt
	v_pk_mul_f32 v[62:63], v[62:63], v[142:143] op_sel_hi:[1,0]
	v_pk_mul_f32 v[54:55], v[54:55], v[142:143] op_sel_hi:[1,0]
	v_lshl_add_u64 v[64:65], v[72:73], 0, s[18:19]
	v_pk_mul_f32 v[66:67], v[58:59], v[142:143] op_sel_hi:[1,0]
	v_pk_mul_f32 v[58:59], v[56:57], v[142:143] op_sel_hi:[1,0]
	s_waitcnt lgkmcnt(0)
	global_store_dwordx4 v[64:65], v[68:71], off nt
	v_cvt_pk_bf16_f32 v56, v60, v61
	v_cvt_pk_bf16_f32 v57, v62, v63
	v_cvt_pk_bf16_f32 v58, v58, v59
	v_cvt_pk_bf16_f32 v59, v66, v67
	v_pk_mul_f32 v[60:61], v[50:51], v[142:143] op_sel_hi:[1,0]
	v_pk_mul_f32 v[50:51], v[48:49], v[142:143] op_sel_hi:[1,0]
	v_pk_mul_f32 v[52:53], v[52:53], v[142:143] op_sel_hi:[1,0]
	v_rsq_f32_e32 v140, v153
	v_cvt_pk_bf16_f32 v48, v52, v53
	v_cvt_pk_bf16_f32 v49, v54, v55
	v_cvt_pk_bf16_f32 v50, v50, v51
	v_cvt_pk_bf16_f32 v51, v60, v61
	ds_write_b128 v148, v[56:59]
	ds_write_b128 v148, v[48:51] offset:64
	ds_read_b128 v[48:51], v149
	ds_read_b128 v[52:55], v149 offset:1152
	v_add_co_u32_e32 v56, vcc, s79, v138
	v_lshl_add_u64 v[64:65], v[138:139], 0, s[46:47]
	s_nop 0
	v_addc_co_u32_e32 v57, vcc, 0, v139, vcc
	s_waitcnt lgkmcnt(1)
	global_store_dwordx4 v[56:57], v[48:51], off nt
	v_pk_mul_f32 v[44:45], v[44:45], v[140:141] op_sel_hi:[1,0]
	v_pk_mul_f32 v[46:47], v[46:47], v[140:141] op_sel_hi:[1,0]
	v_lshl_add_u64 v[48:49], v[64:65], 0, s[18:19]
	s_waitcnt lgkmcnt(0)
	global_store_dwordx4 v[48:49], v[52:55], off nt
	v_pk_mul_f32 v[48:49], v[42:43], v[140:141] op_sel_hi:[1,0]
	v_pk_mul_f32 v[42:43], v[40:41], v[140:141] op_sel_hi:[1,0]
	v_cvt_pk_bf16_f32 v40, v44, v45
	v_cvt_pk_bf16_f32 v41, v46, v47
	v_pk_mul_f32 v[44:45], v[34:35], v[140:141] op_sel_hi:[1,0]
	v_cvt_pk_bf16_f32 v42, v42, v43
	v_cvt_pk_bf16_f32 v43, v48, v49
	v_pk_mul_f32 v[34:35], v[32:33], v[140:141] op_sel_hi:[1,0]
	v_pk_mul_f32 v[38:39], v[38:39], v[140:141] op_sel_hi:[1,0]
	v_pk_mul_f32 v[36:37], v[36:37], v[140:141] op_sel_hi:[1,0]
	v_rsq_f32_e32 v132, v155
	v_cvt_pk_bf16_f32 v32, v36, v37
	v_cvt_pk_bf16_f32 v33, v38, v39
	v_cvt_pk_bf16_f32 v34, v34, v35
	v_cvt_pk_bf16_f32 v35, v44, v45
	ds_write_b128 v148, v[40:43]
	ds_write_b128 v148, v[32:35] offset:64
	ds_read_b128 v[32:35], v149
	ds_read_b128 v[36:39], v149 offset:1152
	v_lshl_add_u64 v[40:41], v[64:65], 0, s[40:41]
	v_pk_mul_f32 v[28:29], v[28:29], v[132:133] op_sel_hi:[1,0]
	s_waitcnt lgkmcnt(1)
	global_store_dwordx4 v[40:41], v[32:35], off nt
	v_pk_mul_f32 v[30:31], v[30:31], v[132:133] op_sel_hi:[1,0]
	v_pk_mul_f32 v[22:23], v[22:23], v[132:133] op_sel_hi:[1,0]
	v_lshl_add_u64 v[32:33], v[40:41], 0, s[18:19]
	s_waitcnt lgkmcnt(0)
	global_store_dwordx4 v[32:33], v[36:39], off nt
	v_pk_mul_f32 v[32:33], v[26:27], v[132:133] op_sel_hi:[1,0]
	v_pk_mul_f32 v[26:27], v[24:25], v[132:133] op_sel_hi:[1,0]
	v_cvt_pk_bf16_f32 v24, v28, v29
	v_cvt_pk_bf16_f32 v25, v30, v31
	v_pk_mul_f32 v[28:29], v[18:19], v[132:133] op_sel_hi:[1,0]
	v_cvt_pk_bf16_f32 v26, v26, v27
	v_cvt_pk_bf16_f32 v27, v32, v33
	v_pk_mul_f32 v[18:19], v[16:17], v[132:133] op_sel_hi:[1,0]
	v_pk_mul_f32 v[20:21], v[20:21], v[132:133] op_sel_hi:[1,0]
	v_fmamk_f32 v42, v120, 0x3b800000, v147
	v_cvt_pk_bf16_f32 v16, v20, v21
	v_cvt_pk_bf16_f32 v17, v22, v23
	v_cvt_pk_bf16_f32 v18, v18, v19
	v_cvt_pk_bf16_f32 v19, v28, v29
	ds_write_b128 v148, v[24:27]
	ds_write_b128 v148, v[16:19] offset:64
	ds_read_b128 v[16:19], v149
	ds_read_b128 v[20:23], v149 offset:1152
	v_rsq_f32_e32 v24, v42
	v_lshl_add_u64 v[26:27], v[64:65], 0, s[42:43]
	s_waitcnt lgkmcnt(1)
	global_store_dwordx4 v[26:27], v[16:19], off nt
	v_pk_mul_f32 v[12:13], v[12:13], v[24:25] op_sel_hi:[1,0]
	v_pk_mul_f32 v[14:15], v[14:15], v[24:25] op_sel_hi:[1,0]
	v_lshl_add_u64 v[16:17], v[26:27], 0, s[18:19]
	s_waitcnt lgkmcnt(0)
	global_store_dwordx4 v[16:17], v[20:23], off nt
	v_pk_mul_f32 v[16:17], v[10:11], v[24:25] op_sel_hi:[1,0]
	v_pk_mul_f32 v[10:11], v[8:9], v[24:25] op_sel_hi:[1,0]
	v_cvt_pk_bf16_f32 v8, v12, v13
	v_cvt_pk_bf16_f32 v9, v14, v15
	v_pk_mul_f32 v[12:13], v[2:3], v[24:25] op_sel_hi:[1,0]
	v_cvt_pk_bf16_f32 v10, v10, v11
	v_cvt_pk_bf16_f32 v11, v16, v17
	v_pk_mul_f32 v[2:3], v[0:1], v[24:25] op_sel_hi:[1,0]
	v_pk_mul_f32 v[6:7], v[6:7], v[24:25] op_sel_hi:[1,0]
	v_pk_mul_f32 v[4:5], v[4:5], v[24:25] op_sel_hi:[1,0]
	s_andn2_b64 vcc, exec, s[4:5]
	v_cvt_pk_bf16_f32 v0, v4, v5
	v_cvt_pk_bf16_f32 v1, v6, v7
	v_cvt_pk_bf16_f32 v2, v2, v3
	v_cvt_pk_bf16_f32 v3, v12, v13
	ds_write_b128 v148, v[8:11]
	ds_write_b128 v148, v[0:3] offset:64
	ds_read_b128 v[0:3], v149
	ds_read_b128 v[4:7], v149 offset:1152
	v_lshl_add_u64 v[8:9], v[64:65], 0, s[44:45]
	s_mov_b64 s[4:5], -1
	s_waitcnt lgkmcnt(1)
	global_store_dwordx4 v[8:9], v[0:3], off nt
	s_nop 1
	v_lshl_add_u64 v[0:1], v[8:9], 0, s[18:19]
	s_waitcnt lgkmcnt(0)
	global_store_dwordx4 v[0:1], v[4:7], off nt
	s_cbranch_vccnz .LBB0_736
	s_andn2_b64 vcc, exec, s[8:9]
	s_cbranch_vccnz .LBB0_735
	s_barrier
	s_branch .LBB0_735
